# GQA loop: first PV group's V transposed reads issued under the QK tail into the free K/V prefetch registers, K/V global prefetch issued behind the first PV group
# speedup vs baseline: 1.0007x; 1.0007x over previous
; #define SBAR() __builtin_amdgcn_sched_barrier(0)
; #define SLOAD(i, k0) do { sr_[i].vs0 = *(const bf16x8*)(&Vh[(long)((k0) + sr) * LDK + sc]); sr_[i].vs1 = *(const bf16x8*)(&Vh[(long)((k0) + 32 + sr) * LDK + sc]); \
;     sr_[i].ks0 = *(const bf16x8*)(&Kh[(long)((k0) + sr) * LDK + sc]); sr_[i].ks1 = *(const bf16x8*)(&Kh[(long)((k0) + 32 + sr) * LDK + sc]); } while (0)
; template <int D0> __device__ __forceinline__ void pv_one(f32x16& od, int vb, bf16x8 pa0, bf16x8 pa1, bf16x8 pa2, bf16x8 pa3) {
;   const s16x4 l0 = tr_read<v_rd_off(D0, 0, 0)>(vb), h0 = tr_read<v_rd_off(D0, 0, 1)>(vb), l1 = tr_read<v_rd_off(D0, 1, 0)>(vb), h1 = tr_read<v_rd_off(D0, 1, 1)>(vb);
;   const s16x4 l2 = tr_read<v_rd_off(D0, 2, 0)>(vb), h2 = tr_read<v_rd_off(D0, 2, 1)>(vb), l3 = tr_read<v_rd_off(D0, 3, 0)>(vb), h3 = tr_read<v_rd_off(D0, 3, 1)>(vb);
;   asm volatile("s_waitcnt lgkmcnt(0)" ::: "memory"); SBAR();
;     ...
;   od = __builtin_amdgcn_mfma_f32_32x32x16_bf16(pa0, PK(l0, h0), od, 0, 0, 0);
;   od = __builtin_amdgcn_mfma_f32_32x32x16_bf16(pa1, PK(l1, h1), od, 0, 0, 0);
;   od = __builtin_amdgcn_mfma_f32_32x32x16_bf16(pa2, PK(l2, h2), od, 0, 0, 0);
;   od = __builtin_amdgcn_mfma_f32_32x32x16_bf16(pa3, PK(l3, h3), od, 0, 0, 0);
; template <int MODE, int SDEPTH, bool SIMPLE>
; __device__ __forceinline__ void attn_body(const Unit& U, char* lds, const int tid) {
;     ...
;     SBAR(); qkt(pB0, pB1, K_lds + SHM_K, qr, r32, hi); amask<MODE>(pB0, pB1, j, U, wid, r32, hi, tbl);
;     finishSM(pA0, pA1, alA, l_reg, pa0, pa1, pa2, pa3); SBAR();
;     SLOAD(SO, (j + SDEPTH) * KVBLK); SBAR();
;     pv_d0(o, vb0, pa0, pa1, pa2, pa3); partialSM(pB0, pB1, m_reg, mnB, alB);
.LBB0_199:
	ds_read_b128 v[64:67], v204 offset:49152
	ds_read_b128 v[68:71], v204 offset:57344
	ds_read_b128 v[220:223], v211 offset:49152
	ds_read_b128 v[234:237], v211 offset:57344
	v_add_f32_e32 v160, 0, v161
	v_add_f32_e32 v160, v162, v160
	s_waitcnt lgkmcnt(3)
	v_mfma_f32_32x32x16_bf16 v[80:95], v[64:67], v[116:119], 0
	v_add_f32_e32 v160, v174, v160
	v_add_f32_e32 v160, v175, v160
	v_add_f32_e32 v160, v216, v160
	v_add_f32_e32 v160, v219, v160
	v_add_f32_e32 v160, v163, v160
	v_add_f32_e32 v160, v173, v160
	v_add_f32_e32 v160, v168, v160
	s_waitcnt lgkmcnt(2)
	v_mfma_f32_32x32x16_bf16 v[64:79], v[68:71], v[116:119], 0
	v_add_f32_e32 v160, v170, v160
	v_add_f32_e32 v160, v171, v160
	v_add_f32_e32 v160, v172, v160
	v_exp_f32_e32 v156, v156
	v_add_f32_e32 v160, v165, v160
	v_exp_f32_e32 v157, v157
	v_add_f32_e32 v160, v166, v160
	s_waitcnt lgkmcnt(1)
	v_mfma_f32_32x32x16_bf16 v[80:95], v[220:223], v[112:115], v[80:95]
	v_exp_f32_e32 v154, v154
	v_add_f32_e32 v160, v167, v160
	v_exp_f32_e32 v155, v155
	v_add_f32_e32 v160, v169, v160
	v_exp_f32_e32 v148, v148
	v_add_f32_e32 v160, v156, v160
	v_exp_f32_e32 v149, v149
	s_waitcnt lgkmcnt(0)
	v_mfma_f32_32x32x16_bf16 v[64:79], v[234:237], v[112:115], v[64:79]
	ds_read_b128 v[220:223], v210 offset:49152
	ds_read_b128 v[234:237], v210 offset:57344
	v_add_f32_e32 v160, v157, v160
	v_exp_f32_e32 v146, v146
	v_add_f32_e32 v160, v154, v160
	v_exp_f32_e32 v147, v147
	v_add_f32_e32 v160, v155, v160
	v_exp_f32_e32 v144, v144
	s_waitcnt lgkmcnt(1)
	v_mfma_f32_32x32x16_bf16 v[80:95], v[220:223], v[124:127], v[80:95]
	v_add_f32_e32 v160, v148, v160
	v_exp_f32_e32 v145, v145
	v_add_f32_e32 v160, v149, v160
	v_exp_f32_e32 v158, v158
	v_add_f32_e32 v160, v146, v160
	v_exp_f32_e32 v159, v159
	v_add_f32_e32 v160, v147, v160
	s_waitcnt lgkmcnt(0)
	v_mfma_f32_32x32x16_bf16 v[64:79], v[234:237], v[124:127], v[64:79]
	ds_read_b128 v[220:223], v208 offset:49152
	ds_read_b128 v[234:237], v208 offset:57344
	v_exp_f32_e32 v152, v152
	v_add_f32_e32 v160, v144, v160
	v_exp_f32_e32 v153, v153
	v_add_f32_e32 v160, v145, v160
	v_exp_f32_e32 v150, v150
	v_add_f32_e32 v160, v158, v160
	s_waitcnt lgkmcnt(1)
	v_mfma_f32_32x32x16_bf16 v[80:95], v[220:223], v[120:123], v[80:95]
	v_exp_f32_e32 v151, v151
	v_add_f32_e32 v160, v159, v160
	v_add_f32_e32 v160, v152, v160
	v_add_f32_e32 v160, v153, v160
	v_add_f32_e32 v160, v150, v160
	v_add_f32_e32 v213, v151, v160
	v_mov_b32_e32 v214, v213
	s_waitcnt lgkmcnt(0)
	v_mfma_f32_32x32x16_bf16 v[64:79], v[234:237], v[120:123], v[64:79]
	ds_read_b128 v[220:223], v206 offset:49152
	ds_read_b128 v[234:237], v206 offset:57344
	v_cvt_pk_bf16_f32 v160, v161, v162
	v_cvt_pk_bf16_f32 v162, v216, v219
	v_permlane32_swap_b32_e32 v213, v214
	v_cvt_pk_bf16_f32 v161, v174, v175
	v_cvt_pk_bf16_f32 v163, v163, v173
	s_waitcnt lgkmcnt(1)
	v_mfma_f32_32x32x16_bf16 v[80:95], v[220:223], v[108:111], v[80:95]
	v_permlane32_swap_b32_e32 v160, v162
	v_cvt_pk_bf16_f32 v170, v168, v170
	v_cvt_pk_bf16_f32 v171, v171, v172
	v_cvt_pk_bf16_f32 v172, v165, v166
	v_cvt_pk_bf16_f32 v173, v167, v169
	v_cvt_pk_bf16_f32 v166, v156, v157
	s_waitcnt lgkmcnt(0)
	v_mfma_f32_32x32x16_bf16 v[64:79], v[234:237], v[108:111], v[64:79]
	ds_read_b128 v[220:223], v205 offset:49152
	ds_read_b128 v[234:237], v205 offset:57344
	v_cvt_pk_bf16_f32 v167, v154, v155
	v_cvt_pk_bf16_f32 v168, v148, v149
	v_cvt_pk_bf16_f32 v169, v146, v147
	v_cvt_pk_bf16_f32 v216, v144, v145
	v_cvt_pk_bf16_f32 v217, v158, v159
	v_cvt_pk_bf16_f32 v218, v152, v153
	s_waitcnt lgkmcnt(1)
	v_mfma_f32_32x32x16_bf16 v[80:95], v[220:223], v[104:107], v[80:95]
	v_cvt_pk_bf16_f32 v219, v150, v151
	v_permlane32_swap_b32_e32 v161, v163
	v_permlane32_swap_b32_e32 v170, v172
	v_permlane32_swap_b32_e32 v171, v173
	s_waitcnt lgkmcnt(0)
	v_mfma_f32_32x32x16_bf16 v[64:79], v[234:237], v[104:107], v[64:79]
	ds_read_b64_tr_b16 v[144:145], v189 offset:0
	ds_read_b64_tr_b16 v[146:147], v189 offset:0x800
	ds_read_b64_tr_b16 v[148:149], v189 offset:0x1000
	ds_read_b64_tr_b16 v[150:151], v189 offset:0x1800
	ds_read_b64_tr_b16 v[152:153], v189 offset:0x2000
	ds_read_b64_tr_b16 v[154:155], v189 offset:0x2800
	ds_read_b64_tr_b16 v[156:157], v189 offset:0x3000
	ds_read_b64_tr_b16 v[158:159], v189 offset:0x3800
	ds_read_b128 v[220:223], v207 offset:49152
	ds_read_b128 v[234:237], v207 offset:57344
	v_permlane32_swap_b32_e32 v166, v168
	v_permlane32_swap_b32_e32 v167, v169
	v_permlane32_swap_b32_e32 v216, v218
	s_waitcnt lgkmcnt(1)
	v_mfma_f32_32x32x16_bf16 v[80:95], v[220:223], v[100:103], v[80:95]
	v_permlane32_swap_b32_e32 v217, v219
	s_waitcnt lgkmcnt(0)
	v_mfma_f32_32x32x16_bf16 v[64:79], v[234:237], v[100:103], v[64:79]
	ds_read_b128 v[220:223], v209 offset:49152
	ds_read_b128 v[234:237], v209 offset:57344
	s_waitcnt lgkmcnt(1)
	v_mfma_f32_32x32x16_bf16 v[80:95], v[220:223], v[96:99], v[80:95]
	s_waitcnt lgkmcnt(0)
	v_mfma_f32_32x32x16_bf16 v[64:79], v[234:237], v[96:99], v[64:79]
	s_waitcnt lgkmcnt(0)
	s_nop 0
	v_mfma_f32_32x32x16_bf16 v[0:15], v[160:163], v[144:147], v[0:15]
	ds_read_b64_tr_b16 v[220:221], v189 offset:0x200
	ds_read_b64_tr_b16 v[222:223], v189 offset:0xa00
	v_mfma_f32_32x32x16_bf16 v[0:15], v[170:173], v[148:151], v[0:15]
	ds_read_b64_tr_b16 v[234:235], v189 offset:0x1200
	ds_read_b64_tr_b16 v[236:237], v189 offset:0x1a00
	v_mfma_f32_32x32x16_bf16 v[0:15], v[166:169], v[152:155], v[0:15]
	ds_read_b64_tr_b16 v[238:239], v189 offset:0x2200
	ds_read_b64_tr_b16 v[240:241], v189 offset:0x2a00
	v_mfma_f32_32x32x16_bf16 v[0:15], v[216:219], v[156:159], v[0:15]
	ds_read_b64_tr_b16 v[242:243], v189 offset:0x3200
	ds_read_b64_tr_b16 v[244:245], v189 offset:0x3a00
	s_movk_i32 s0, 0xa000
	v_add_co_u32_e32 v144, vcc, s0, v178
	s_movk_i32 s0, 0xc000
	s_nop 0
	v_addc_co_u32_e32 v145, vcc, -1, v179, vcc
	v_add_co_u32_e32 v148, vcc, s0, v178
	s_mov_b32 s0, 0xff7fa000
	s_nop 0
	v_addc_co_u32_e32 v149, vcc, -1, v179, vcc
	v_add_co_u32_e32 v152, vcc, s0, v178
	s_mov_b32 s0, 0xff7fc000
	s_nop 0
	v_addc_co_u32_e32 v153, vcc, -1, v179, vcc
	v_add_co_u32_e32 v156, vcc, s0, v178
	global_load_dwordx4 v[144:147], v[144:145], off
	s_nop 0
	global_load_dwordx4 v[148:151], v[148:149], off
	v_addc_co_u32_e32 v157, vcc, -1, v179, vcc
	global_load_dwordx4 v[152:155], v[152:153], off
	s_nop 0
	global_load_dwordx4 v[156:159], v[156:157], off
	s_waitcnt lgkmcnt(0)
; #define SWRITE(b, i) do { *(bf16x8*)(V_lds + (b) * SHM_V + vst0) = sr_[i].vs0;          \
;     *(bf16x8*)(V_lds + (b) * SHM_V + vst1) = sr_[i].vs1; int kc = sc * 2;               \
;     *(bf16x8*)(K_lds + (b) * SHM_K + KSWZ(sr, kc)) = sr_[i].ks0;                       \
;     *(bf16x8*)(K_lds + (b) * SHM_K + KSWZ(32 + sr, kc)) = sr_[i].ks1; } while (0)
; #define SWAIT() do { if constexpr (SDEPTH == 2) asm volatile("s_waitcnt vmcnt(4)" ::: "memory"); else asm volatile("s_waitcnt vmcnt(0)" ::: "memory"); } while (0)
; #define RESC(a) do { if (__any((a) < 1.f)) { if (hi == 0) al_l[r32] = (a); asm volatile("s_waitcnt lgkmcnt(0)" ::: "memory"); \
;     _Pragma("unroll") for (int d = 0; d < 4; ++d) _Pragma("unroll") for (int r = 0; r < 16; ++r) o[d][r] *= al_l[crow(r, hi)]; } } while (0)
; __device__ __forceinline__ void partialSM(f32x16& p0, f32x16& p1, float& m_reg, float& mn, float& alpha) {
;   constexpr float C = SCALE * 1.4426950408889634f;
;   float pmax = p0[0];
; #pragma unroll
;   for (int r = 1; r < 16; ++r) pmax = fmaxf(pmax, p0[r]);
; #pragma unroll
;   for (int r = 0; r < 16; ++r) pmax = fmaxf(pmax, p1[r]);
;   { auto rr = __builtin_amdgcn_permlane32_swap(__float_as_uint(pmax), __float_as_uint(pmax), false, false);
;     pmax = fmaxf(__uint_as_float(rr[0]), __uint_as_float(rr[1])); }
;   if (__builtin_expect(__all(pmax - m_reg <= THR / SCALE), 1)) { mn = m_reg; alpha = 1.f; }
;   else { mn = fmaxf(m_reg, pmax); alpha = __builtin_amdgcn_exp2f((m_reg - mn) * C); m_reg = mn; }
; template <int MODE, int SDEPTH, bool SIMPLE>
; __device__ __forceinline__ void attn_body(const Unit& U, char* lds, const int tid) {
;     ...
;     pv_d0(o, vb0, pa0, pa1, pa2, pa3); partialSM(pB0, pB1, m_reg, mnB, alB);
;     __syncthreads(); SWAIT(); SWRITE(0, SE);
;     RESC(alB); __syncthreads();
	v_mfma_f32_32x32x16_bf16 v[48:63], v[160:163], v[220:223], v[48:63]
	ds_read_b64_tr_b16 v[220:221], v189 offset:0x400
	ds_read_b64_tr_b16 v[222:223], v189 offset:0xc00
	v_mfma_f32_32x32x16_bf16 v[48:63], v[170:173], v[234:237], v[48:63]
	ds_read_b64_tr_b16 v[234:235], v189 offset:0x1400
	ds_read_b64_tr_b16 v[236:237], v189 offset:0x1c00
	v_mfma_f32_32x32x16_bf16 v[48:63], v[166:169], v[238:241], v[48:63]
	ds_read_b64_tr_b16 v[238:239], v189 offset:0x2400
	ds_read_b64_tr_b16 v[240:241], v189 offset:0x2c00
	v_mfma_f32_32x32x16_bf16 v[48:63], v[216:219], v[242:245], v[48:63]
	ds_read_b64_tr_b16 v[242:243], v189 offset:0x3400
	ds_read_b64_tr_b16 v[244:245], v189 offset:0x3c00
	s_waitcnt lgkmcnt(0)
	v_mfma_f32_32x32x16_bf16 v[32:47], v[160:163], v[220:223], v[32:47]
	ds_read_b64_tr_b16 v[220:221], v189 offset:0x600
	ds_read_b64_tr_b16 v[222:223], v189 offset:0xe00
	v_mfma_f32_32x32x16_bf16 v[32:47], v[170:173], v[234:237], v[32:47]
	ds_read_b64_tr_b16 v[234:235], v189 offset:0x1600
	ds_read_b64_tr_b16 v[236:237], v189 offset:0x1e00
	v_mfma_f32_32x32x16_bf16 v[32:47], v[166:169], v[238:241], v[32:47]
	ds_read_b64_tr_b16 v[238:239], v189 offset:0x2600
	ds_read_b64_tr_b16 v[240:241], v189 offset:0x2e00
	v_mfma_f32_32x32x16_bf16 v[32:47], v[216:219], v[242:245], v[32:47]
	ds_read_b64_tr_b16 v[242:243], v189 offset:0x3600
	ds_read_b64_tr_b16 v[244:245], v189 offset:0x3e00
	s_waitcnt lgkmcnt(0)
	v_mfma_f32_32x32x16_bf16 v[16:31], v[160:163], v[220:223], v[16:31]
	v_max_f32_e32 v160, v81, v81
	v_max_f32_e32 v161, v80, v80
	v_max_f32_e32 v160, v161, v160
	v_max3_f32 v160, v160, v82, v83
	v_max3_f32 v160, v160, v84, v85
	v_max3_f32 v160, v160, v86, v87
	v_max3_f32 v160, v160, v88, v89
	v_max3_f32 v160, v160, v90, v91
	v_max3_f32 v160, v160, v92, v93
	v_mfma_f32_32x32x16_bf16 v[16:31], v[170:173], v[234:237], v[16:31]
	v_max3_f32 v160, v160, v94, v95
	v_max3_f32 v160, v160, v64, v65
	v_max3_f32 v160, v160, v66, v67
	v_max3_f32 v160, v160, v68, v69
	v_max3_f32 v160, v160, v70, v71
	v_max3_f32 v160, v160, v72, v73
	v_max3_f32 v160, v160, v74, v75
	v_max3_f32 v160, v160, v76, v77
	v_mfma_f32_32x32x16_bf16 v[16:31], v[166:169], v[238:241], v[16:31]
	v_max3_f32 v160, v160, v78, v79
	v_mov_b32_e32 v161, v160
	s_nop 1
	v_permlane32_swap_b32_e32 v160, v161
	v_max_f32_e32 v161, v161, v161
	v_max_f32_e32 v160, v160, v160
	v_max_f32_e32 v160, v160, v161
	v_sub_f32_e32 v161, v160, v164
	v_cmp_ge_f32_e32 vcc, s18, v161
	v_max_f32_e32 v161, v164, v164
	v_max_f32_e32 v160, v161, v160
	v_mfma_f32_32x32x16_bf16 v[16:31], v[216:219], v[242:245], v[16:31]
	v_sub_f32_e32 v161, v164, v160
	v_mul_f32_e32 v161, 0x3e0293ee, v161
	v_exp_f32_e32 v161, v161
	s_cmp_eq_u64 vcc, exec
	s_cselect_b64 s[0:1], -1, 0
	s_barrier
	s_waitcnt vmcnt(4)
	v_cndmask_b32_e64 v215, v161, 1.0, s[0:1]
	v_cmp_gt_f32_e32 vcc, 1.0, v215
	s_waitcnt vmcnt(7)
	ds_write_b128 v191, v[128:131]
	s_waitcnt vmcnt(6)
	ds_write_b128 v202, v[136:139]
	s_waitcnt vmcnt(5)
	ds_write_b128 v190, v[132:135] offset:32768
	s_waitcnt vmcnt(4)
	ds_write_b128 v203, v[140:143] offset:32768
	s_cbranch_vccz .LBB0_203
	s_and_saveexec_b64 s[2:3], s[36:37]
	ds_write_b32 v186, v215 offset:128
	s_or_b64 exec, exec, s[2:3]
	s_waitcnt lgkmcnt(0)
	v_add_u32_e32 v161, v185, v192
	ds_read_b128 v[166:169], v161 offset:224
	ds_read_b128 v[170:173], v161 offset:192
	ds_read_b128 v[216:219], v161 offset:160
	ds_read_b128 v[220:223], v161 offset:128
	s_waitcnt lgkmcnt(3)
	v_pk_mul_f32 v[12:13], v[12:13], v[166:167]
	s_waitcnt lgkmcnt(2)
	v_pk_mul_f32 v[8:9], v[8:9], v[170:171]
	s_waitcnt lgkmcnt(1)
	v_pk_mul_f32 v[4:5], v[4:5], v[216:217]
	v_pk_mul_f32 v[14:15], v[14:15], v[168:169]
	v_pk_mul_f32 v[10:11], v[10:11], v[172:173]
	v_pk_mul_f32 v[6:7], v[6:7], v[218:219]
	s_waitcnt lgkmcnt(0)
	v_pk_mul_f32 v[2:3], v[2:3], v[222:223]
	v_pk_mul_f32 v[0:1], v[0:1], v[220:221]
	v_pk_mul_f32 v[60:61], v[60:61], v[166:167]
	v_pk_mul_f32 v[56:57], v[56:57], v[170:171]
	v_pk_mul_f32 v[52:53], v[52:53], v[216:217]
	v_pk_mul_f32 v[62:63], v[62:63], v[168:169]
	v_pk_mul_f32 v[58:59], v[58:59], v[172:173]
	v_pk_mul_f32 v[54:55], v[54:55], v[218:219]
	v_pk_mul_f32 v[50:51], v[50:51], v[222:223]
	v_pk_mul_f32 v[48:49], v[48:49], v[220:221]
	v_pk_mul_f32 v[44:45], v[44:45], v[166:167]
	v_pk_mul_f32 v[40:41], v[40:41], v[170:171]
	v_pk_mul_f32 v[36:37], v[36:37], v[216:217]
	v_pk_mul_f32 v[46:47], v[46:47], v[168:169]
	v_pk_mul_f32 v[42:43], v[42:43], v[172:173]
	v_pk_mul_f32 v[38:39], v[38:39], v[218:219]
	v_pk_mul_f32 v[34:35], v[34:35], v[222:223]
	v_pk_mul_f32 v[32:33], v[32:33], v[220:221]
	v_pk_mul_f32 v[28:29], v[28:29], v[166:167]
	v_pk_mul_f32 v[24:25], v[24:25], v[170:171]
	v_pk_mul_f32 v[20:21], v[20:21], v[216:217]
	v_pk_mul_f32 v[30:31], v[30:31], v[168:169]
	v_pk_mul_f32 v[26:27], v[26:27], v[172:173]
	v_pk_mul_f32 v[22:23], v[22:23], v[218:219]
	v_pk_mul_f32 v[18:19], v[18:19], v[222:223]
	v_pk_mul_f32 v[16:17], v[16:17], v[220:221]
; #define SBAR() __builtin_amdgcn_sched_barrier(0)
; __device__ __forceinline__ void partialSM(f32x16& p0, f32x16& p1, float& m_reg, float& mn, float& alpha) {
;     ...
;   float mnC = -mn * C;
; #pragma unroll
;   for (int r = 0; r < 16; ++r) p0[r] = fmaf(p0[r], C, mnC);
; #pragma unroll
;   for (int r = 0; r < 16; ++r) p1[r] = fmaf(p1[r], C, mnC);
; #pragma unroll
;   for (int r = 0; r < 16; ++r) p0[r] = __builtin_amdgcn_exp2f(p0[r]);
; }
; __device__ __forceinline__ void finishSM(f32x16& p0, f32x16& p1, float alpha, float& l_reg, bf16x8& pa0, bf16x8& pa1, bf16x8& pa2, bf16x8& pa3) {
; #pragma unroll
;   for (int r = 0; r < 16; ++r) p1[r] = __builtin_amdgcn_exp2f(p1[r]);
;   float ps = 0;
; #pragma unroll
;   for (int r = 0; r < 16; ++r) ps += p0[r];
; #pragma unroll
;   for (int r = 0; r < 16; ++r) ps += p1[r];
;   { auto rr = __builtin_amdgcn_permlane32_swap(__float_as_uint(ps), __float_as_uint(ps), false, false);
;     ps = __uint_as_float(rr[0]) + __uint_as_float(rr[1]); }
; template <int MODE, int SDEPTH, bool SIMPLE>
; __device__ __forceinline__ void attn_body(const Unit& U, char* lds, const int tid) {
;     ...
;     SBAR(); qkt(pA0, pA1, K_lds, qr, r32, hi); amask<MODE>(pA0, pA1, j + 1, U, wid, r32, hi, tbl);
;     finishSM(pB0, pB1, alB, l_reg, pa0, pa1, pa2, pa3); SBAR();
.LBB0_203:
	v_cndmask_b32_e64 v216, v160, v164, s[0:1]
	v_mul_f32_e32 v217, 0xbe0293ee, v216
	v_fmamk_f32 v80, v80, 0x3e0293ee, v217
	v_fmamk_f32 v81, v81, 0x3e0293ee, v217
	v_fmamk_f32 v82, v82, 0x3e0293ee, v217
	v_fmamk_f32 v83, v83, 0x3e0293ee, v217
	v_fmamk_f32 v84, v84, 0x3e0293ee, v217
	v_fmamk_f32 v85, v85, 0x3e0293ee, v217
	v_fmamk_f32 v86, v86, 0x3e0293ee, v217
	v_fmamk_f32 v87, v87, 0x3e0293ee, v217
	v_fmamk_f32 v88, v88, 0x3e0293ee, v217
	v_fmamk_f32 v89, v89, 0x3e0293ee, v217
	v_fmamk_f32 v90, v90, 0x3e0293ee, v217
	v_fmamk_f32 v91, v91, 0x3e0293ee, v217
	v_fmamk_f32 v92, v92, 0x3e0293ee, v217
	v_fmamk_f32 v93, v93, 0x3e0293ee, v217
	v_fmamk_f32 v94, v94, 0x3e0293ee, v217
	v_fmamk_f32 v95, v95, 0x3e0293ee, v217
	v_exp_f32_e32 v160, v80
	v_exp_f32_e32 v161, v81
	v_exp_f32_e32 v162, v82
	v_exp_f32_e32 v173, v83
	v_exp_f32_e32 v174, v84
	v_exp_f32_e32 v175, v85
	v_exp_f32_e32 v163, v86
	v_exp_f32_e32 v172, v87
	v_exp_f32_e32 v164, v88
	v_exp_f32_e32 v165, v89
	v_exp_f32_e32 v170, v90
	v_exp_f32_e32 v171, v91
	v_exp_f32_e32 v166, v92
	v_exp_f32_e32 v167, v93
	v_exp_f32_e32 v168, v94
	v_exp_f32_e32 v169, v95
	v_fmamk_f32 v235, v64, 0x3e0293ee, v217
	v_fmamk_f32 v236, v65, 0x3e0293ee, v217
	v_fmamk_f32 v237, v66, 0x3e0293ee, v217
	v_fmamk_f32 v238, v67, 0x3e0293ee, v217
	v_fmamk_f32 v239, v68, 0x3e0293ee, v217
	v_fmamk_f32 v219, v69, 0x3e0293ee, v217
	v_fmamk_f32 v220, v70, 0x3e0293ee, v217
	v_fmamk_f32 v221, v71, 0x3e0293ee, v217
	v_fmamk_f32 v222, v72, 0x3e0293ee, v217
	v_fmamk_f32 v223, v73, 0x3e0293ee, v217
	v_fmamk_f32 v233, v74, 0x3e0293ee, v217
	v_fmamk_f32 v234, v75, 0x3e0293ee, v217
	v_fmamk_f32 v218, v76, 0x3e0293ee, v217
	v_fmamk_f32 v240, v77, 0x3e0293ee, v217
	v_fmamk_f32 v241, v78, 0x3e0293ee, v217
	v_fmac_f32_e32 v217, 0x3e0293ee, v79
	s_waitcnt lgkmcnt(0)
	s_barrier
	ds_read_b128 v[64:67], v204 offset:32768
	ds_read_b128 v[68:71], v204 offset:40960
	ds_read_b128 v[242:245], v211 offset:32768
	ds_read_b128 v[246:249], v211 offset:40960
	v_exp_f32_e32 v235, v235
	v_exp_f32_e32 v236, v236
	s_waitcnt lgkmcnt(3)
	v_mfma_f32_32x32x16_bf16 v[80:95], v[64:67], v[116:119], 0
	v_exp_f32_e32 v237, v237
	v_exp_f32_e32 v238, v238
	v_exp_f32_e32 v239, v239
	v_exp_f32_e32 v219, v219
	v_exp_f32_e32 v220, v220
	v_exp_f32_e32 v221, v221
	v_exp_f32_e32 v222, v222
	s_waitcnt lgkmcnt(2)
	v_mfma_f32_32x32x16_bf16 v[64:79], v[68:71], v[116:119], 0
	v_exp_f32_e32 v223, v223
	v_exp_f32_e32 v233, v233
	v_exp_f32_e32 v234, v234
	v_exp_f32_e32 v240, v240
	v_exp_f32_e32 v241, v241
	s_waitcnt lgkmcnt(1)
	v_mfma_f32_32x32x16_bf16 v[80:95], v[242:245], v[112:115], v[80:95]
	s_waitcnt lgkmcnt(0)
	v_mfma_f32_32x32x16_bf16 v[64:79], v[246:249], v[112:115], v[64:79]
	ds_read_b128 v[242:245], v210 offset:32768
	ds_read_b128 v[246:249], v210 offset:40960
	s_waitcnt lgkmcnt(1)
	v_mfma_f32_32x32x16_bf16 v[80:95], v[242:245], v[124:127], v[80:95]
	s_waitcnt lgkmcnt(0)
	v_mfma_f32_32x32x16_bf16 v[64:79], v[246:249], v[124:127], v[64:79]
	ds_read_b128 v[242:245], v208 offset:32768
	ds_read_b128 v[246:249], v208 offset:40960
	s_waitcnt lgkmcnt(1)
	v_mfma_f32_32x32x16_bf16 v[80:95], v[242:245], v[120:123], v[80:95]
	s_waitcnt lgkmcnt(0)
	v_mfma_f32_32x32x16_bf16 v[64:79], v[246:249], v[120:123], v[64:79]
	ds_read_b128 v[242:245], v206 offset:32768
	ds_read_b128 v[246:249], v206 offset:40960
	s_waitcnt lgkmcnt(1)
	v_mfma_f32_32x32x16_bf16 v[80:95], v[242:245], v[108:111], v[80:95]
	s_waitcnt lgkmcnt(0)
	v_mfma_f32_32x32x16_bf16 v[64:79], v[246:249], v[108:111], v[64:79]
	ds_read_b128 v[242:245], v205 offset:32768
	ds_read_b128 v[246:249], v205 offset:40960
	s_waitcnt lgkmcnt(1)
	v_mfma_f32_32x32x16_bf16 v[80:95], v[242:245], v[104:107], v[80:95]
	s_waitcnt lgkmcnt(0)
	v_mfma_f32_32x32x16_bf16 v[64:79], v[246:249], v[104:107], v[64:79]
	ds_read_b64_tr_b16 v[128:129], v188 offset:0
	ds_read_b64_tr_b16 v[130:131], v188 offset:0x800
	ds_read_b64_tr_b16 v[132:133], v188 offset:0x1000
	ds_read_b64_tr_b16 v[134:135], v188 offset:0x1800
	ds_read_b64_tr_b16 v[136:137], v188 offset:0x2000
	ds_read_b64_tr_b16 v[138:139], v188 offset:0x2800
	ds_read_b64_tr_b16 v[140:141], v188 offset:0x3000
	ds_read_b64_tr_b16 v[142:143], v188 offset:0x3800
	ds_read_b128 v[242:245], v207 offset:32768
	ds_read_b128 v[246:249], v207 offset:40960
	s_waitcnt lgkmcnt(1)
	v_mfma_f32_32x32x16_bf16 v[80:95], v[242:245], v[100:103], v[80:95]
	s_waitcnt lgkmcnt(0)
	v_mfma_f32_32x32x16_bf16 v[64:79], v[246:249], v[100:103], v[64:79]
	ds_read_b128 v[242:245], v209 offset:32768
	ds_read_b128 v[246:249], v209 offset:40960
	s_waitcnt lgkmcnt(1)
	v_mfma_f32_32x32x16_bf16 v[80:95], v[242:245], v[96:99], v[80:95]
	v_exp_f32_e32 v243, v217
	v_add_f32_e32 v217, 0, v160
	v_add_f32_e32 v217, v161, v217
	v_add_f32_e32 v217, v162, v217
	v_add_f32_e32 v217, v173, v217
	v_add_f32_e32 v217, v174, v217
	v_add_f32_e32 v217, v175, v217
	v_add_f32_e32 v217, v163, v217
	v_add_f32_e32 v217, v172, v217
	v_add_f32_e32 v217, v164, v217
	v_add_f32_e32 v217, v165, v217
	v_add_f32_e32 v217, v170, v217
	v_add_f32_e32 v217, v171, v217
	v_add_f32_e32 v217, v166, v217
	v_add_f32_e32 v217, v167, v217
	v_add_f32_e32 v217, v168, v217
	v_add_f32_e32 v217, v169, v217
	v_add_f32_e32 v217, v235, v217
	v_add_f32_e32 v217, v236, v217
	v_add_f32_e32 v217, v237, v217
	v_add_f32_e32 v217, v238, v217
	v_add_f32_e32 v217, v239, v217
	v_add_f32_e32 v217, v219, v217
	v_add_f32_e32 v217, v220, v217
	v_add_f32_e32 v217, v221, v217
	v_exp_f32_e32 v242, v218
	v_add_f32_e32 v217, v222, v217
	v_add_f32_e32 v217, v223, v217
	s_waitcnt lgkmcnt(0)
; #define SBAR() __builtin_amdgcn_sched_barrier(0)
; __device__ __forceinline__ void finishSM(f32x16& p0, f32x16& p1, float alpha, float& l_reg, bf16x8& pa0, bf16x8& pa1, bf16x8& pa2, bf16x8& pa3) {
;     ...
;   for (int r = 0; r < 16; ++r) ps += p0[r];
; #pragma unroll
;   for (int r = 0; r < 16; ++r) ps += p1[r];
;   { auto rr = __builtin_amdgcn_permlane32_swap(__float_as_uint(ps), __float_as_uint(ps), false, false);
;     ps = __uint_as_float(rr[0]) + __uint_as_float(rr[1]); }
;   l_reg = l_reg * alpha + ps;
;     ...
;   PK4(p0, 0, pa0); PK4(p0, 8, pa1); PK4(p1, 0, pa2); PK4(p1, 8, pa3);
; template <int D0> __device__ __forceinline__ void pv_one(f32x16& od, int vb, bf16x8 pa0, bf16x8 pa1, bf16x8 pa2, bf16x8 pa3) {
;   const s16x4 l0 = tr_read<v_rd_off(D0, 0, 0)>(vb), h0 = tr_read<v_rd_off(D0, 0, 1)>(vb), l1 = tr_read<v_rd_off(D0, 1, 0)>(vb), h1 = tr_read<v_rd_off(D0, 1, 1)>(vb);
;   const s16x4 l2 = tr_read<v_rd_off(D0, 2, 0)>(vb), h2 = tr_read<v_rd_off(D0, 2, 1)>(vb), l3 = tr_read<v_rd_off(D0, 3, 0)>(vb), h3 = tr_read<v_rd_off(D0, 3, 1)>(vb);
;   asm volatile("s_waitcnt lgkmcnt(0)" ::: "memory"); SBAR();
;     ...
;   od = __builtin_amdgcn_mfma_f32_32x32x16_bf16(pa0, PK(l0, h0), od, 0, 0, 0);
;   od = __builtin_amdgcn_mfma_f32_32x32x16_bf16(pa1, PK(l1, h1), od, 0, 0, 0);
;   od = __builtin_amdgcn_mfma_f32_32x32x16_bf16(pa2, PK(l2, h2), od, 0, 0, 0);
;   od = __builtin_amdgcn_mfma_f32_32x32x16_bf16(pa3, PK(l3, h3), od, 0, 0, 0);
	v_mfma_f32_32x32x16_bf16 v[64:79], v[246:249], v[96:99], v[64:79]
	v_add_f32_e32 v217, v233, v217
	v_add_f32_e32 v217, v234, v217
	v_add_f32_e32 v217, v242, v217
	v_add_f32_e32 v217, v240, v217
	v_add_f32_e32 v217, v241, v217
	v_add_f32_e32 v217, v243, v217
	v_mov_b32_e32 v218, v217
	v_cvt_pk_bf16_f32 v160, v160, v161
	v_cvt_pk_bf16_f32 v161, v162, v173
	v_cvt_pk_bf16_f32 v162, v174, v175
	v_cvt_pk_bf16_f32 v163, v163, v172
	v_cvt_pk_bf16_f32 v164, v164, v165
	v_cvt_pk_bf16_f32 v165, v170, v171
	v_cvt_pk_bf16_f32 v166, v166, v167
	v_cvt_pk_bf16_f32 v167, v168, v169
	v_cvt_pk_bf16_f32 v168, v235, v236
	v_cvt_pk_bf16_f32 v169, v237, v238
	v_cvt_pk_bf16_f32 v170, v239, v219
	v_cvt_pk_bf16_f32 v171, v220, v221
	v_cvt_pk_bf16_f32 v172, v222, v223
	v_cvt_pk_bf16_f32 v173, v233, v234
	v_cvt_pk_bf16_f32 v174, v242, v240
	v_cvt_pk_bf16_f32 v175, v241, v243
	v_permlane32_swap_b32_e32 v217, v218
	v_permlane32_swap_b32_e32 v160, v162
	v_permlane32_swap_b32_e32 v161, v163
	v_permlane32_swap_b32_e32 v164, v166
	v_permlane32_swap_b32_e32 v165, v167
	v_permlane32_swap_b32_e32 v168, v170
	v_permlane32_swap_b32_e32 v169, v171
	v_permlane32_swap_b32_e32 v172, v174
	v_permlane32_swap_b32_e32 v173, v175
	s_waitcnt lgkmcnt(0)
	s_nop 0
	v_mfma_f32_32x32x16_bf16 v[0:15], v[160:163], v[128:131], v[0:15]
	ds_read_b64_tr_b16 v[220:221], v188 offset:0x200
	ds_read_b64_tr_b16 v[222:223], v188 offset:0xa00
	v_mfma_f32_32x32x16_bf16 v[0:15], v[164:167], v[132:135], v[0:15]
	ds_read_b64_tr_b16 v[234:235], v188 offset:0x1200
	ds_read_b64_tr_b16 v[236:237], v188 offset:0x1a00
	v_mfma_f32_32x32x16_bf16 v[0:15], v[168:171], v[136:139], v[0:15]
	ds_read_b64_tr_b16 v[238:239], v188 offset:0x2200
	ds_read_b64_tr_b16 v[240:241], v188 offset:0x2a00
	v_mfma_f32_32x32x16_bf16 v[0:15], v[172:175], v[140:143], v[0:15]
	ds_read_b64_tr_b16 v[242:243], v188 offset:0x3200
	ds_read_b64_tr_b16 v[244:245], v188 offset:0x3a00
	s_cmpk_gt_u32 s20, 0x7c
	s_cselect_b64 s[2:3], -1, 0
	s_and_b64 vcc, exec, s[2:3]
	s_cbranch_vccnz .Lgq_noprefetch
	v_add_co_u32_e32 v128, vcc, 0xffffe000, v178
	s_nop 1
	v_addc_co_u32_e32 v129, vcc, -1, v179, vcc
	v_add_co_u32_e32 v132, vcc, 0xff7fe000, v178
	s_nop 1
	v_addc_co_u32_e32 v133, vcc, -1, v179, vcc
	v_add_co_u32_e32 v140, vcc, 0xff800000, v178
	global_load_dwordx4 v[128:131], v[128:129], off
	s_nop 0
	global_load_dwordx4 v[132:135], v[132:133], off
	v_addc_co_u32_e32 v141, vcc, -1, v179, vcc
	global_load_dwordx4 v[136:139], v[178:179], off
	s_nop 0
	global_load_dwordx4 v[140:143], v[140:141], off
; #define SBAR() __builtin_amdgcn_sched_barrier(0)
; __device__ __forceinline__ void partialSM(f32x16& p0, f32x16& p1, float& m_reg, float& mn, float& alpha) {
;   constexpr float C = SCALE * 1.4426950408889634f;
;   float pmax = p0[0];
; #pragma unroll
;   for (int r = 1; r < 16; ++r) pmax = fmaxf(pmax, p0[r]);
; #pragma unroll
;   for (int r = 0; r < 16; ++r) pmax = fmaxf(pmax, p1[r]);
;   { auto rr = __builtin_amdgcn_permlane32_swap(__float_as_uint(pmax), __float_as_uint(pmax), false, false);
;     pmax = fmaxf(__uint_as_float(rr[0]), __uint_as_float(rr[1])); }
;   if (__builtin_expect(__all(pmax - m_reg <= THR / SCALE), 1)) { mn = m_reg; alpha = 1.f; }
;   else { mn = fmaxf(m_reg, pmax); alpha = __builtin_amdgcn_exp2f((m_reg - mn) * C); m_reg = mn; }
; template <int D0> __device__ __forceinline__ void pv_one(f32x16& od, int vb, bf16x8 pa0, bf16x8 pa1, bf16x8 pa2, bf16x8 pa3) {
;   const s16x4 l0 = tr_read<v_rd_off(D0, 0, 0)>(vb), h0 = tr_read<v_rd_off(D0, 0, 1)>(vb), l1 = tr_read<v_rd_off(D0, 1, 0)>(vb), h1 = tr_read<v_rd_off(D0, 1, 1)>(vb);
;   const s16x4 l2 = tr_read<v_rd_off(D0, 2, 0)>(vb), h2 = tr_read<v_rd_off(D0, 2, 1)>(vb), l3 = tr_read<v_rd_off(D0, 3, 0)>(vb), h3 = tr_read<v_rd_off(D0, 3, 1)>(vb);
;   asm volatile("s_waitcnt lgkmcnt(0)" ::: "memory"); SBAR();
;     ...
;   od = __builtin_amdgcn_mfma_f32_32x32x16_bf16(pa0, PK(l0, h0), od, 0, 0, 0);
;   od = __builtin_amdgcn_mfma_f32_32x32x16_bf16(pa1, PK(l1, h1), od, 0, 0, 0);
;   od = __builtin_amdgcn_mfma_f32_32x32x16_bf16(pa2, PK(l2, h2), od, 0, 0, 0);
;   od = __builtin_amdgcn_mfma_f32_32x32x16_bf16(pa3, PK(l3, h3), od, 0, 0, 0);
;     ...
; }
; __device__ __forceinline__ void pv_d0(f32x16* o, int vb, bf16x8 pa0, bf16x8 pa1, bf16x8 pa2, bf16x8 pa3) {
;   pv_one<0>(o[0], vb, pa0, pa1, pa2, pa3); pv_one<1>(o[1], vb, pa0, pa1, pa2, pa3); pv_one<2>(o[2], vb, pa0, pa1, pa2, pa3); pv_one<3>(o[3], vb, pa0, pa1, pa2, pa3);
.LBB0_205:
	s_waitcnt lgkmcnt(0)
	v_mfma_f32_32x32x16_bf16 v[48:63], v[160:163], v[220:223], v[48:63]
	ds_read_b64_tr_b16 v[220:221], v188 offset:0x400
	ds_read_b64_tr_b16 v[222:223], v188 offset:0xc00
	v_mfma_f32_32x32x16_bf16 v[48:63], v[164:167], v[234:237], v[48:63]
	ds_read_b64_tr_b16 v[234:235], v188 offset:0x1400
	ds_read_b64_tr_b16 v[236:237], v188 offset:0x1c00
	v_mfma_f32_32x32x16_bf16 v[48:63], v[168:171], v[238:241], v[48:63]
	ds_read_b64_tr_b16 v[238:239], v188 offset:0x2400
	ds_read_b64_tr_b16 v[240:241], v188 offset:0x2c00
	v_mfma_f32_32x32x16_bf16 v[48:63], v[172:175], v[242:245], v[48:63]
	ds_read_b64_tr_b16 v[242:243], v188 offset:0x3400
	ds_read_b64_tr_b16 v[244:245], v188 offset:0x3c00
	s_waitcnt lgkmcnt(0)
	v_mfma_f32_32x32x16_bf16 v[32:47], v[160:163], v[220:223], v[32:47]
	ds_read_b64_tr_b16 v[220:221], v188 offset:0x600
	ds_read_b64_tr_b16 v[222:223], v188 offset:0xe00
	v_mfma_f32_32x32x16_bf16 v[32:47], v[164:167], v[234:237], v[32:47]
	ds_read_b64_tr_b16 v[234:235], v188 offset:0x1600
	ds_read_b64_tr_b16 v[236:237], v188 offset:0x1e00
	v_mfma_f32_32x32x16_bf16 v[32:47], v[168:171], v[238:241], v[32:47]
	ds_read_b64_tr_b16 v[238:239], v188 offset:0x2600
	ds_read_b64_tr_b16 v[240:241], v188 offset:0x2e00
	v_mfma_f32_32x32x16_bf16 v[32:47], v[172:175], v[242:245], v[32:47]
	ds_read_b64_tr_b16 v[242:243], v188 offset:0x3600
	ds_read_b64_tr_b16 v[244:245], v188 offset:0x3e00
	s_waitcnt lgkmcnt(0)
	v_mfma_f32_32x32x16_bf16 v[16:31], v[160:163], v[220:223], v[16:31]
	v_max_f32_e32 v160, v81, v81
	v_max_f32_e32 v161, v80, v80
	v_max_f32_e32 v160, v161, v160
	v_max3_f32 v160, v160, v82, v83
	v_max3_f32 v160, v160, v84, v85
	v_max3_f32 v160, v160, v86, v87
	v_max3_f32 v160, v160, v88, v89
	v_max3_f32 v160, v160, v90, v91
	v_max3_f32 v160, v160, v92, v93
	v_mfma_f32_32x32x16_bf16 v[16:31], v[164:167], v[234:237], v[16:31]
	v_max3_f32 v160, v160, v94, v95
	v_max3_f32 v160, v160, v64, v65
	v_max3_f32 v160, v160, v66, v67
	v_max3_f32 v160, v160, v68, v69
	v_max3_f32 v160, v160, v70, v71
	v_max3_f32 v160, v160, v72, v73
	v_max3_f32 v160, v160, v74, v75
	v_max3_f32 v160, v160, v76, v77
	v_mfma_f32_32x32x16_bf16 v[16:31], v[168:171], v[238:241], v[16:31]
	v_max3_f32 v160, v160, v78, v79
	v_mov_b32_e32 v161, v160
	s_nop 1
	v_permlane32_swap_b32_e32 v160, v161
	v_max_f32_e32 v161, v161, v161
	v_max_f32_e32 v160, v160, v160
	v_max_f32_e32 v160, v160, v161
	v_sub_f32_e32 v161, v160, v216
	v_cmp_ge_f32_e32 vcc, s18, v161
	v_max_f32_e32 v161, v216, v216
	v_max_f32_e32 v161, v161, v160
	v_mfma_f32_32x32x16_bf16 v[16:31], v[172:175], v[242:245], v[16:31]
	v_sub_f32_e32 v160, v216, v161
	v_mul_f32_e32 v160, 0x3e0293ee, v160
	v_exp_f32_e32 v160, v160
	s_cmp_eq_u64 vcc, exec
	s_cselect_b64 s[0:1], -1, 0
	s_barrier
	s_waitcnt vmcnt(4)
	v_cndmask_b32_e64 v160, v160, 1.0, s[0:1]
	v_cmp_gt_f32_e32 vcc, 1.0, v160
	ds_write_b128 v191, v[144:147] offset:16384
	ds_write_b128 v202, v[148:151] offset:16384
	ds_write_b128 v190, v[152:155] offset:49152
	ds_write_b128 v203, v[156:159] offset:49152
	s_cbranch_vccz .LBB0_209
	s_and_saveexec_b64 s[42:43], s[36:37]
	ds_write_b32 v186, v160 offset:128
	s_or_b64 exec, exec, s[42:43]
	s_waitcnt lgkmcnt(0)
	v_add_u32_e32 v156, v185, v192
	ds_read_b128 v[144:147], v156 offset:224
	ds_read_b128 v[148:151], v156 offset:192
	ds_read_b128 v[152:155], v156 offset:160
	ds_read_b128 v[156:159], v156 offset:128
	s_waitcnt lgkmcnt(3)
	v_pk_mul_f32 v[12:13], v[12:13], v[144:145]
	s_waitcnt lgkmcnt(2)
	v_pk_mul_f32 v[8:9], v[8:9], v[148:149]
	s_waitcnt lgkmcnt(1)
	v_pk_mul_f32 v[4:5], v[4:5], v[152:153]
	v_pk_mul_f32 v[14:15], v[14:15], v[146:147]
	v_pk_mul_f32 v[10:11], v[10:11], v[150:151]
	v_pk_mul_f32 v[6:7], v[6:7], v[154:155]
	s_waitcnt lgkmcnt(0)
	v_pk_mul_f32 v[2:3], v[2:3], v[158:159]
	v_pk_mul_f32 v[0:1], v[0:1], v[156:157]
	v_pk_mul_f32 v[60:61], v[60:61], v[144:145]
	v_pk_mul_f32 v[56:57], v[56:57], v[148:149]
	v_pk_mul_f32 v[52:53], v[52:53], v[152:153]
	v_pk_mul_f32 v[62:63], v[62:63], v[146:147]
	v_pk_mul_f32 v[58:59], v[58:59], v[150:151]
	v_pk_mul_f32 v[54:55], v[54:55], v[154:155]
	v_pk_mul_f32 v[50:51], v[50:51], v[158:159]
	v_pk_mul_f32 v[48:49], v[48:49], v[156:157]
	v_pk_mul_f32 v[44:45], v[44:45], v[144:145]
	v_pk_mul_f32 v[40:41], v[40:41], v[148:149]
	v_pk_mul_f32 v[36:37], v[36:37], v[152:153]
	v_pk_mul_f32 v[46:47], v[46:47], v[146:147]
	v_pk_mul_f32 v[42:43], v[42:43], v[150:151]
	v_pk_mul_f32 v[38:39], v[38:39], v[154:155]
	v_pk_mul_f32 v[34:35], v[34:35], v[158:159]
	v_pk_mul_f32 v[32:33], v[32:33], v[156:157]
	v_pk_mul_f32 v[28:29], v[28:29], v[144:145]
	v_pk_mul_f32 v[24:25], v[24:25], v[148:149]
	v_pk_mul_f32 v[20:21], v[20:21], v[152:153]
	v_pk_mul_f32 v[30:31], v[30:31], v[146:147]
	v_pk_mul_f32 v[26:27], v[26:27], v[150:151]
	v_pk_mul_f32 v[22:23], v[22:23], v[154:155]
	v_pk_mul_f32 v[18:19], v[18:19], v[158:159]
	v_pk_mul_f32 v[16:17], v[16:17], v[156:157]
